# GEMM2: every other CU of each XCD starts the phase 5 us late so memory-bound epilogues overlap the other half's MFMA main loops
# speedup vs baseline: 1.0111x; 1.0111x over previous
.LBB0_623:
	s_cmp_lt_i32 s64, 5
	s_cselect_b64 s[8:9], -1, 0
	s_and_b64 s[0:1], s[8:9], s[0:1]
	s_cmpk_lt_i32 s2, 0x300
	s_cselect_b64 s[6:7], -1, 0
	s_and_b64 s[0:1], s[0:1], s[6:7]
	s_andn2_b64 vcc, exec, s[0:1]
	s_cbranch_vccnz .LBB0_632
	s_and_b32 s0, s62, 7
	s_cmp_lg_u32 s0, 0
	s_cselect_b64 s[0:1], -1, 0
	s_ashr_i32 s18, s62, 3
	s_add_u32 s19, s96, 0x720000
	s_addc_u32 s20, s97, 0
	s_add_u32 s21, s96, 0x13a0000
	s_addc_u32 s22, s97, 0
	s_add_u32 s10, s96, 0x43a0000
	s_addc_u32 s11, s97, 0
	s_add_u32 s23, s96, 0xecc4000
	s_addc_u32 s24, s97, 0
	s_abs_i32 s25, s62
	v_cvt_f32_u32_e32 v2, s25
	v_cndmask_b32_e64 v1, 0, 1, s[0:1]
	s_sub_i32 s0, 0, s25
	s_mov_b64 s[12:13], s[36:37]
	v_rcp_iflag_f32_e32 v2, v2
	v_mbcnt_hi_u32_b32 v89, -1, v213
	s_lshl_b32 s28, s62, 3
	s_mov_b64 s[14:15], s[38:39]
	v_mul_f32_e32 v2, 0x4f7ffffe, v2
	v_cvt_u32_f32_e32 v2, v2
	s_ashr_i32 s26, s62, 31
	s_sub_i32 s27, 0, s62
	s_lshl_b32 s29, s2, 3
	v_readfirstlane_b32 s1, v2
	s_mul_i32 s0, s0, s1
	s_mul_hi_u32 s0, s1, s0
	v_and_b32_e32 v2, 64, v89
	s_sub_i32 s30, 0, s28
	s_add_i32 s31, s1, s0
	v_cmp_ne_u32_e64 s[0:1], 1, v1
	v_mov_b32_e32 v67, 0
	s_movk_i32 s34, 0x90
	s_mov_b32 s35, 0xfffffc0
	s_mov_b32 s36, 0x20000
	s_mov_b32 s37, 0x40000
	s_mov_b32 s38, 0x60000
	s_movk_i32 s39, 0xff00
	s_movk_i32 s40, 0x410
	s_movk_i32 s41, 0x2000
	v_mov_b32_e32 v1, s15
	v_mov_b32_e32 v86, s13
	v_mov_b32_e32 v87, s14
	v_mov_b32_e32 v88, s12
	s_movk_i32 s42, 0x1000
	v_add_u32_e32 v90, 64, v2
	v_xor_b32_e32 v91, 32, v89
	v_xor_b32_e32 v92, 16, v89
	v_xor_b32_e32 v93, 8, v89
	v_xor_b32_e32 v94, 4, v89
	v_xor_b32_e32 v95, 2, v89
	v_xor_b32_e32 v96, 1, v89
	s_bitcmp1_b32 s2, 3
	s_cbranch_scc0 .Lskew_done_g2
	s_memrealtime s[98:99]
	s_waitcnt lgkmcnt(0)
	s_add_u32 s100, s98, 500
.Lskew_loop_g2:
	s_sleep 8
	s_memrealtime s[98:99]
	s_waitcnt lgkmcnt(0)
	s_sub_u32 s99, s98, s100
	s_cmp_lt_i32 s99, 0
	s_cbranch_scc1 .Lskew_loop_g2
.Lskew_done_g2:
	s_mov_b32 s43, s2
	s_branch .LBB0_626
